# work-queue pulls: ticket atomic issued before the workgroup barrier that closes the previous unit, result consumed after it (both queue loops)
# speedup vs baseline: 1.0038x; 1.0038x over previous
; __device__ __forceinline__ int tid_opaque() { int t = threadIdx.x; asm volatile("" : "+v"(t)); return t; }
; __global__ void __launch_bounds__(NT, 2) fwd_megakernel(Params p) {
;     ...
;             for (;;) {
;                 __syncthreads();
;                 const int t3_ = tid_opaque();
;                 if (t3_ == 0) *qslot = __hip_atomic_fetch_add(qc, 1u, __ATOMIC_RELAXED, __HIP_MEMORY_SCOPE_AGENT);
;                 __syncthreads();
;                 int u = (int)*qslot;
;                 if (u >= n_state + n_vt + n_rope) break;
.LBB0_378:
	v_mov_b32_e32 v106, v165
	v_cmp_eq_u32_e32 vcc, 0, v106
	s_and_saveexec_b64 s[0:1], vcc
	s_cbranch_execz .Lq1_issued
	v_mov_b32_e32 v2, 1
	global_atomic_add v2, v1, v2, s[8:9] sc0
.Lq1_issued:
	s_or_b64 exec, exec, s[0:1]
	s_barrier
	s_and_saveexec_b64 s[0:1], vcc
	s_cbranch_execz .LBB0_382
	s_waitcnt vmcnt(0)
	v_readfirstlane_b32 s2, v2
	s_nop 1
	v_mov_b32_e32 v0, s2
	v_readlane_b32 s2, v254, 24
	s_nop 1
	v_mov_b32_e32 v2, s2
	ds_write_b32 v2, v0

; __device__ __forceinline__ int tid_opaque() { int t = threadIdx.x; asm volatile("" : "+v"(t)); return t; }
; __global__ void __launch_bounds__(NT, 2) fwd_megakernel(Params p) {
;     ...
;             for (;;) {
;                 __syncthreads();
;                 if (tid_opaque() == 0) *qslot = __hip_atomic_fetch_add(qc, 1u, __ATOMIC_RELAXED, __HIP_MEMORY_SCOPE_AGENT);
;                 __syncthreads();
;                 int u = (int)*qslot;
.LBB0_657:
	v_mov_b32_e32 v0, v165
	v_cmp_eq_u32_e32 vcc, 0, v0
	s_and_saveexec_b64 s[0:1], vcc
	s_cbranch_execz .Lq2_issued
	v_readlane_b32 s4, v254, 45
	v_readlane_b32 s5, v254, 46
	v_mov_b32_e32 v2, 1
	s_nop 4
	global_atomic_add v2, v1, v2, s[4:5] sc0
